# run prologue also issues the second K-tile's A(1,1) half (16 stage loads up front, waits vmcnt(10)/(8)); on top of v039
# baseline (speedup 1.0000x reference)
.Lstag_done:
.LBB0_772:
	s_lshl_b32 s0, s75, 6
	s_add_i32 s0, s0, 0
	s_add_i32 s0, s0, 0x21400
	v_mov_b32_e32 v2, s0
	s_waitcnt lgkmcnt(0)
	ds_read2_b32 v[4:5], v2 offset0:9 offset1:10
	ds_read2_b32 v[6:7], v2 offset0:11 offset1:12
	ds_read2_b32 v[8:9], v2 offset0:13 offset1:14
	ds_read_b32 v2, v2 offset:60
	s_abs_i32 s0, s85
	s_waitcnt lgkmcnt(0)
	v_readfirstlane_b32 s88, v5
	v_cvt_f32_u32_e32 v5, s0
	s_sub_i32 s8, 0, s0
	s_waitcnt lgkmcnt(0)
	v_readfirstlane_b32 s12, v2
	v_readfirstlane_b32 s1, v4
	v_rcp_iflag_f32_e32 v2, v5
	s_ashr_i32 s1, s1, 1
	s_abs_i32 s7, s1
	s_xor_b32 s6, s1, s85
	v_mul_f32_e32 v2, 0x4f7ffffe, v2
	v_cvt_u32_f32_e32 v2, v2
	s_ashr_i32 s6, s6, 31
	v_readfirstlane_b32 s10, v8
	v_readfirstlane_b32 s11, v7
	v_readfirstlane_b32 s9, v2
	s_mul_i32 s8, s8, s9
	s_mul_hi_u32 s8, s9, s8
	s_add_i32 s9, s9, s8
	s_mul_hi_u32 s8, s7, s9
	s_mul_i32 s9, s8, s0
	s_sub_i32 s7, s7, s9
	s_add_i32 s9, s8, 1
	s_sub_i32 s14, s7, s0
	s_cmp_ge_u32 s7, s0
	s_cselect_b32 s8, s9, s8
	s_cselect_b32 s7, s14, s7
	s_add_i32 s9, s8, 1
	s_cmp_ge_u32 s7, s0
	s_cselect_b32 s0, s9, s8
	s_xor_b32 s0, s0, s6
	s_sub_i32 s6, s0, s6
	s_mul_i32 s0, s6, s85
	s_sub_i32 s7, s1, s0
	s_min_i32 s0, s67, s7
	s_mul_i32 s1, s6, s67
	s_ashr_i32 s8, s4, 31
	s_add_i32 s0, s0, s1
	s_mul_i32 s8, s8, s88
	s_mul_hi_u32 s9, s4, s88
	s_lshl_b32 s0, s0, 1
	s_mov_b32 s1, s41
	s_add_i32 s9, s9, s8
	s_mul_i32 s8, s4, s88
	s_lshl_b64 s[0:1], s[0:1], 7
	s_lshl_b64 s[8:9], s[8:9], 8
	s_add_u32 s8, 0, s8
	s_addc_u32 s9, s10, s9
	s_add_u32 s8, s8, s11
	s_addc_u32 s9, s9, 0
	s_add_u32 s90, s8, s0
	v_readfirstlane_b32 s86, v6
	s_addc_u32 s91, s9, s1
	s_ashr_i32 s8, s3, 31
	s_mul_i32 s8, s8, s86
	s_mul_hi_u32 s9, s3, s86
	s_add_i32 s9, s9, s8
	s_mul_i32 s8, s3, s86
	s_lshl_b64 s[8:9], s[8:9], 8
	s_add_u32 s8, 0, s8
	v_readfirstlane_b32 s13, v9
	s_addc_u32 s9, s12, s9
	s_add_u32 s8, s8, s13
	s_addc_u32 s9, s9, 0
	s_add_u32 s52, s8, s0
	s_addc_u32 s53, s9, s1
	s_add_i32 s78, s5, 0
	s_mov_b32 s89, s41
	s_mov_b32 s87, s41
	v_mad_u64_u32 v[196:197], s[0:1], s88, v235, v[192:193]
	v_mad_u64_u32 v[198:199], s[0:1], s86, v238, v[192:193]
	v_mad_u64_u32 v[200:201], s[0:1], s88, v240, v[194:195]
	v_mad_u64_u32 v[202:203], s[0:1], s86, v242, v[194:195]
	s_add_i32 m0, s78, 0x10000
	s_lshl_b64 s[8:9], s[88:89], 7
	global_load_lds_dwordx4 v198, s[52:53]
	s_add_i32 m0, s78, 0x12000
	s_lshl_b64 s[0:1], s[86:87], 7
	s_add_u32 s0, s52, s0
	global_load_lds_dwordx4 v202, s[52:53]
	s_addc_u32 s1, s53, s1
	s_add_i32 m0, s78, 0x14000
	s_add_i32 s87, s78, 0x2000
	global_load_lds_dwordx4 v198, s[0:1]
	s_add_i32 m0, s78, 0x16000
	s_add_u32 s8, s90, s8
	global_load_lds_dwordx4 v202, s[0:1]
	s_mov_b32 m0, s78
	s_addc_u32 s9, s91, s9
	global_load_lds_dwordx4 v196, s[90:91]
	s_mov_b32 m0, s87
	s_add_i32 s79, s78, 0x4000
	global_load_lds_dwordx4 v200, s[90:91]
	s_mov_b32 m0, s79
	s_add_i32 s34, s78, 0x6000
	global_load_lds_dwordx4 v196, s[8:9]
	s_mov_b32 m0, s34
	s_nop 0
	global_load_lds_dwordx4 v200, s[8:9]
	s_add_u32 s8, s8, 0x80
	s_addc_u32 s9, s9, 0
	s_add_i32 m0, s78, 0xc000
	s_nop 0
	global_load_lds_dwordx4 v196, s[8:9]
	s_add_i32 m0, s78, 0xe000
	s_nop 0
	global_load_lds_dwordx4 v200, s[8:9]
	v_readlane_b32 s8, v255, 19
	v_readlane_b32 s9, v255, 20
	s_andn2_b64 vcc, exec, s[8:9]
	s_nop 0
	v_cndmask_b32_e64 v2, 0, 1, s[8:9]
	v_cmp_ne_u32_e64 s[10:11], 1, v2
	s_nop 1
	v_writelane_b32 v255, s10, 36
	s_nop 1
	v_writelane_b32 v255, s11, 37
	s_cbranch_vccnz .LBB0_774
	s_barrier
.LBB0_774:
	v_mov_b32_e32 v199, v3
	v_mov_b32_e32 v203, v3
	s_cmp_lt_i32 s67, s7
	v_lshl_add_u64 v[8:9], s[0:1], 0, v[198:199]
	v_lshl_add_u64 v[10:11], s[0:1], 0, v[202:203]
	s_cselect_b64 s[0:1], -1, 0
	v_lshl_add_u64 v[4:5], s[52:53], 0, v[198:199]
	s_cmp_lg_u64 s[0:1], 0
	v_lshl_add_u64 v[6:7], s[52:53], 0, v[202:203]
	v_mov_b32_e32 v197, v3
	s_addc_u32 s0, s6, 0
	v_lshl_add_u64 v[4:5], v[4:5], 0, s[60:61]
	s_add_i32 m0, s78, 0x18000
	v_lshl_add_u64 v[12:13], s[90:91], 0, v[196:197]
	v_mov_b32_e32 v201, v3
	global_load_lds_dwordx4 v[4:5], off
	v_lshl_add_u64 v[4:5], v[6:7], 0, s[60:61]
	s_add_i32 m0, s78, 0x1a000
	s_add_i32 s35, s78, 0x8000
	v_lshl_add_u64 v[14:15], s[90:91], 0, v[200:201]
	global_load_lds_dwordx4 v[4:5], off
	v_lshl_add_u64 v[4:5], v[12:13], 0, s[60:61]
	s_mov_b32 m0, s35
	s_add_i32 s46, s78, 0xa000
	global_load_lds_dwordx4 v[4:5], off
	v_lshl_add_u64 v[4:5], v[14:15], 0, s[60:61]
	s_mov_b32 m0, s46
	v_mov_b32_e32 v2, v3
	global_load_lds_dwordx4 v[4:5], off
	v_lshl_add_u64 v[4:5], v[8:9], 0, s[60:61]
	s_add_i32 m0, s78, 0x1c000
	s_lshl_b32 s47, s0, 1
	global_load_lds_dwordx4 v[4:5], off
	v_lshl_add_u64 v[4:5], v[10:11], 0, s[60:61]
	s_add_i32 m0, s78, 0x1e000
	s_nop 0
	global_load_lds_dwordx4 v[4:5], off
	s_waitcnt vmcnt(10)
	s_barrier
	s_waitcnt vmcnt(8)
	v_mov_b32_e32 v4, v3
	v_mov_b32_e32 v5, v3
	v_mov_b64_e32 v[12:13], v[4:5]
	v_mov_b64_e32 v[8:9], v[4:5]
	v_mov_b64_e32 v[20:21], v[4:5]
	v_mov_b64_e32 v[16:17], v[4:5]
	v_mov_b64_e32 v[28:29], v[4:5]
	v_mov_b64_e32 v[24:25], v[4:5]
	v_mov_b64_e32 v[36:37], v[4:5]
	v_mov_b64_e32 v[32:33], v[4:5]
	v_mov_b64_e32 v[44:45], v[4:5]
	v_mov_b64_e32 v[40:41], v[4:5]
	v_mov_b64_e32 v[52:53], v[4:5]
	v_mov_b64_e32 v[48:49], v[4:5]
	v_mov_b64_e32 v[76:77], v[4:5]
	v_mov_b64_e32 v[72:73], v[4:5]
	v_mov_b64_e32 v[84:85], v[4:5]
	v_mov_b64_e32 v[80:81], v[4:5]
	v_mov_b64_e32 v[92:93], v[4:5]
	v_mov_b64_e32 v[88:89], v[4:5]
	v_mov_b64_e32 v[100:101], v[4:5]
	v_mov_b64_e32 v[96:97], v[4:5]
	v_mov_b64_e32 v[108:109], v[4:5]
	v_mov_b64_e32 v[104:105], v[4:5]
	v_mov_b64_e32 v[116:117], v[4:5]
	v_mov_b64_e32 v[112:113], v[4:5]
	v_mov_b64_e32 v[124:125], v[4:5]
	v_mov_b64_e32 v[120:121], v[4:5]
	v_mov_b64_e32 v[132:133], v[4:5]
	v_mov_b64_e32 v[128:129], v[4:5]
	v_mov_b64_e32 v[56:57], v[4:5]
	v_mov_b64_e32 v[64:65], v[4:5]
	v_mov_b64_e32 v[60:61], v[4:5]
	v_mov_b64_e32 v[68:69], v[4:5]
	v_mov_b64_e32 v[10:11], v[2:3]
	v_mov_b64_e32 v[6:7], v[2:3]
	v_mov_b64_e32 v[18:19], v[2:3]
	v_mov_b64_e32 v[14:15], v[2:3]
	v_mov_b64_e32 v[26:27], v[2:3]
	v_mov_b64_e32 v[22:23], v[2:3]
	v_mov_b64_e32 v[34:35], v[2:3]
	v_mov_b64_e32 v[30:31], v[2:3]
	v_mov_b64_e32 v[42:43], v[2:3]
	v_mov_b64_e32 v[38:39], v[2:3]
	v_mov_b64_e32 v[50:51], v[2:3]
	v_mov_b64_e32 v[46:47], v[2:3]
	v_mov_b64_e32 v[74:75], v[2:3]
	v_mov_b64_e32 v[70:71], v[2:3]
	v_mov_b64_e32 v[82:83], v[2:3]
	v_mov_b64_e32 v[78:79], v[2:3]
	v_mov_b64_e32 v[90:91], v[2:3]
	v_mov_b64_e32 v[86:87], v[2:3]
	v_mov_b64_e32 v[98:99], v[2:3]
	v_mov_b64_e32 v[94:95], v[2:3]
	v_mov_b64_e32 v[106:107], v[2:3]
	v_mov_b64_e32 v[102:103], v[2:3]
	v_mov_b64_e32 v[114:115], v[2:3]
	v_mov_b64_e32 v[110:111], v[2:3]
	v_mov_b64_e32 v[122:123], v[2:3]
	v_mov_b64_e32 v[118:119], v[2:3]
	v_mov_b64_e32 v[130:131], v[2:3]
	v_mov_b64_e32 v[126:127], v[2:3]
	v_mov_b64_e32 v[54:55], v[2:3]
	v_mov_b64_e32 v[62:63], v[2:3]
	v_mov_b64_e32 v[58:59], v[2:3]
	v_mov_b64_e32 v[66:67], v[2:3]
	s_barrier
	s_branch .LBB0_777
